# v22 = v21 + NA cross-half max/sum via v_permlane32_swap instead of ds_bpermute
# speedup vs baseline: 1.0003x; 1.0003x over previous
; __device__ __forceinline__ unsigned pk2(float lo, float hi) { return f2bf(lo) | (f2bf(hi) << 16); }
; __device__ __forceinline__ void attn_store(bf16_t* op  , const f32x16& o0, const f32x16& o1, float inv) {
; #pragma unroll
;     for (int a = 0; a < 4; ++a) {
;         u32x2 w; w.x = pk2(o0[4 * a] * inv, o0[4 * a + 1] * inv); w.y = pk2(o0[4 * a + 2] * inv, o0[4 * a + 3] * inv); *(u32x2*)(op + 8 * a) = w;
;         u32x2 x; x.x = pk2(o1[4 * a] * inv, o1[4 * a + 1] * inv); x.y = pk2(o1[4 * a + 2] * inv, o1[4 * a + 3] * inv); *(u32x2*)(op + 32 + 8 * a) = x;
;     }
; }
; __device__ __forceinline__ void na_task4(const PP P, int idx, LAS float* tbl, int lane) {
;     ...
;     lA += __shfl_xor(lA, 32); lB += __shfl_xor(lB, 32);
;     attn_store(MIX + (size_t)qtokA * D + 512 + h * 64 + 4 * hi, oA0, oA1, 1.0f / lA);
;     attn_store(MIX + (size_t)qtokB * D + 512 + h * 64 + 4 * hi, oB0, oB1, 1.0f / lB);
.LBB0_339:
	v_mov_b32_e32 v67, v66
	s_nop 1
	v_permlane32_swap_b32_e32 v67, v66
	s_xor_b64 s[24:25], s[44:45], -1
	s_lshl_b32 s20, s46, 1
	s_mov_b32 s40, 1
	s_waitcnt lgkmcnt(0)
	v_add_f32_e32 v68, v66, v67
	v_div_scale_f32 v70, s[44:45], v68, v68, 1.0
	v_rcp_f32_e32 v71, v70
	v_mov_b32_e32 v66, v218
	s_nop 1
	v_permlane32_swap_b32_e32 v66, v218
	v_fma_f32 v72, -v70, v71, 1.0
	v_fmac_f32_e32 v71, v72, v71
	v_div_scale_f32 v72, vcc, 1.0, v68, 1.0
	v_mul_f32_e32 v73, v72, v71
	v_fma_f32 v74, -v70, v73, v72
	v_fmac_f32_e32 v73, v74, v71
	v_fma_f32 v70, -v70, v73, v72
	v_div_fmas_f32 v70, v70, v71, v73
	s_waitcnt lgkmcnt(0)
	v_add_f32_e32 v69, v218, v66
	v_div_fixup_f32 v68, v70, v68, 1.0
	v_mov_b32_e32 v70, v50
	v_mov_b32_e32 v71, v52
	v_pk_mul_f32 v[70:71], v[70:71], v[68:69] op_sel_hi:[1,0]
	v_mov_b32_e32 v52, v51
	v_pk_mul_f32 v[50:51], v[52:53], v[68:69] op_sel_hi:[1,0]
	v_and_b32_sdwa v52, v71, v243 dst_sel:DWORD dst_unused:UNUSED_PAD src0_sel:WORD_1 src1_sel:DWORD
	v_and_b32_sdwa v53, v70, v243 dst_sel:DWORD dst_unused:UNUSED_PAD src0_sel:WORD_1 src1_sel:DWORD
	v_lshlrev_b64 v[66:67], 11, v[182:183]
	v_add3_u32 v53, v70, v53, s14
	v_add3_u32 v52, v71, v52, s14
	v_and_b32_sdwa v70, v51, v243 dst_sel:DWORD dst_unused:UNUSED_PAD src0_sel:WORD_1 src1_sel:DWORD
	v_and_b32_sdwa v71, v50, v243 dst_sel:DWORD dst_unused:UNUSED_PAD src0_sel:WORD_1 src1_sel:DWORD
	v_lshl_add_u64 v[66:67], s[18:19], 0, v[66:67]
	v_add3_u32 v51, v51, v70, s14
	v_add3_u32 v50, v50, v71, s14
	v_lshl_add_u64 v[66:67], v[66:67], 0, s[20:21]
	v_and_b32_e32 v51, 0xffff0000, v51
	v_and_b32_e32 v50, 0xffff0000, v50
	v_lshl_add_u64 v[66:67], v[66:67], 0, v[0:1]
	v_or_b32_sdwa v51, v51, v52 dst_sel:DWORD dst_unused:UNUSED_PAD src0_sel:DWORD src1_sel:WORD_1
	v_or_b32_sdwa v50, v50, v53 dst_sel:DWORD dst_unused:UNUSED_PAD src0_sel:DWORD src1_sel:WORD_1
	global_store_dwordx2 v[66:67], v[50:51], off offset:1024
	v_mov_b32_e32 v50, v34
	v_mov_b32_e32 v51, v36
	v_pk_mul_f32 v[50:51], v[50:51], v[68:69] op_sel_hi:[1,0]
	v_mov_b32_e32 v36, v35
	v_pk_mul_f32 v[34:35], v[36:37], v[68:69] op_sel_hi:[1,0]
	v_and_b32_sdwa v36, v51, v243 dst_sel:DWORD dst_unused:UNUSED_PAD src0_sel:WORD_1 src1_sel:DWORD
	v_and_b32_sdwa v37, v50, v243 dst_sel:DWORD dst_unused:UNUSED_PAD src0_sel:WORD_1 src1_sel:DWORD
	v_add3_u32 v37, v50, v37, s14
	v_add3_u32 v36, v51, v36, s14
	v_and_b32_sdwa v50, v35, v243 dst_sel:DWORD dst_unused:UNUSED_PAD src0_sel:WORD_1 src1_sel:DWORD
	v_and_b32_sdwa v51, v34, v243 dst_sel:DWORD dst_unused:UNUSED_PAD src0_sel:WORD_1 src1_sel:DWORD
	v_add3_u32 v35, v35, v50, s14
	v_add3_u32 v34, v34, v51, s14
	v_and_b32_e32 v35, 0xffff0000, v35
	v_and_b32_e32 v34, 0xffff0000, v34
	v_or_b32_sdwa v35, v35, v36 dst_sel:DWORD dst_unused:UNUSED_PAD src0_sel:DWORD src1_sel:WORD_1
	v_or_b32_sdwa v34, v34, v37 dst_sel:DWORD dst_unused:UNUSED_PAD src0_sel:DWORD src1_sel:WORD_1
	global_store_dwordx2 v[66:67], v[34:35], off offset:1088
	v_mov_b32_e32 v34, v54
	v_mov_b32_e32 v35, v56
	v_pk_mul_f32 v[34:35], v[34:35], v[68:69] op_sel_hi:[1,0]
	v_mov_b32_e32 v56, v55
	v_pk_mul_f32 v[36:37], v[56:57], v[68:69] op_sel_hi:[1,0]
	v_and_b32_sdwa v50, v35, v243 dst_sel:DWORD dst_unused:UNUSED_PAD src0_sel:WORD_1 src1_sel:DWORD
	v_and_b32_sdwa v51, v34, v243 dst_sel:DWORD dst_unused:UNUSED_PAD src0_sel:WORD_1 src1_sel:DWORD
	v_add3_u32 v34, v34, v51, s14
	v_add3_u32 v35, v35, v50, s14
	v_and_b32_sdwa v50, v37, v243 dst_sel:DWORD dst_unused:UNUSED_PAD src0_sel:WORD_1 src1_sel:DWORD
	v_and_b32_sdwa v51, v36, v243 dst_sel:DWORD dst_unused:UNUSED_PAD src0_sel:WORD_1 src1_sel:DWORD
	v_add3_u32 v37, v37, v50, s14
	v_add3_u32 v36, v36, v51, s14
	v_and_b32_e32 v37, 0xffff0000, v37
	v_and_b32_e32 v36, 0xffff0000, v36
	v_or_b32_sdwa v35, v37, v35 dst_sel:DWORD dst_unused:UNUSED_PAD src0_sel:DWORD src1_sel:WORD_1
	v_or_b32_sdwa v34, v36, v34 dst_sel:DWORD dst_unused:UNUSED_PAD src0_sel:DWORD src1_sel:WORD_1
	global_store_dwordx2 v[66:67], v[34:35], off offset:1040
	v_mov_b32_e32 v34, v38
	v_mov_b32_e32 v35, v40
	v_pk_mul_f32 v[34:35], v[34:35], v[68:69] op_sel_hi:[1,0]
	v_mov_b32_e32 v40, v39
	v_pk_mul_f32 v[36:37], v[40:41], v[68:69] op_sel_hi:[1,0]
	v_and_b32_sdwa v38, v35, v243 dst_sel:DWORD dst_unused:UNUSED_PAD src0_sel:WORD_1 src1_sel:DWORD
	v_and_b32_sdwa v39, v34, v243 dst_sel:DWORD dst_unused:UNUSED_PAD src0_sel:WORD_1 src1_sel:DWORD
	v_add3_u32 v34, v34, v39, s14
	v_add3_u32 v35, v35, v38, s14
	v_and_b32_sdwa v38, v37, v243 dst_sel:DWORD dst_unused:UNUSED_PAD src0_sel:WORD_1 src1_sel:DWORD
	v_and_b32_sdwa v39, v36, v243 dst_sel:DWORD dst_unused:UNUSED_PAD src0_sel:WORD_1 src1_sel:DWORD
	v_add3_u32 v37, v37, v38, s14
	v_add3_u32 v36, v36, v39, s14
	v_and_b32_e32 v37, 0xffff0000, v37
	v_and_b32_e32 v36, 0xffff0000, v36
	v_or_b32_sdwa v35, v37, v35 dst_sel:DWORD dst_unused:UNUSED_PAD src0_sel:DWORD src1_sel:WORD_1
	v_or_b32_sdwa v34, v36, v34 dst_sel:DWORD dst_unused:UNUSED_PAD src0_sel:DWORD src1_sel:WORD_1
	global_store_dwordx2 v[66:67], v[34:35], off offset:1104
	v_mov_b32_e32 v34, v58
	v_mov_b32_e32 v35, v60
	v_pk_mul_f32 v[34:35], v[34:35], v[68:69] op_sel_hi:[1,0]
	v_mov_b32_e32 v60, v59
	v_pk_mul_f32 v[36:37], v[60:61], v[68:69] op_sel_hi:[1,0]
	v_and_b32_sdwa v38, v35, v243 dst_sel:DWORD dst_unused:UNUSED_PAD src0_sel:WORD_1 src1_sel:DWORD
	v_and_b32_sdwa v39, v34, v243 dst_sel:DWORD dst_unused:UNUSED_PAD src0_sel:WORD_1 src1_sel:DWORD
	v_add3_u32 v34, v34, v39, s14
	v_add3_u32 v35, v35, v38, s14
	v_and_b32_sdwa v38, v37, v243 dst_sel:DWORD dst_unused:UNUSED_PAD src0_sel:WORD_1 src1_sel:DWORD
	v_and_b32_sdwa v39, v36, v243 dst_sel:DWORD dst_unused:UNUSED_PAD src0_sel:WORD_1 src1_sel:DWORD
; __device__ __forceinline__ unsigned pk2(float lo, float hi) { return f2bf(lo) | (f2bf(hi) << 16); }
; __device__ __forceinline__ void attn_store(bf16_t* op  , const f32x16& o0, const f32x16& o1, float inv) {
; #pragma unroll
;     for (int a = 0; a < 4; ++a) {
;         u32x2 w; w.x = pk2(o0[4 * a] * inv, o0[4 * a + 1] * inv); w.y = pk2(o0[4 * a + 2] * inv, o0[4 * a + 3] * inv); *(u32x2*)(op + 8 * a) = w;
;         u32x2 x; x.x = pk2(o1[4 * a] * inv, o1[4 * a + 1] * inv); x.y = pk2(o1[4 * a + 2] * inv, o1[4 * a + 3] * inv); *(u32x2*)(op + 32 + 8 * a) = x;
;     }
; }
; __device__ __forceinline__ void na_task4(const PP P, int idx, LAS float* tbl, int lane) {
;     ...
;     attn_store(MIX + (size_t)qtokA * D + 512 + h * 64 + 4 * hi, oA0, oA1, 1.0f / lA);
;     attn_store(MIX + (size_t)qtokB * D + 512 + h * 64 + 4 * hi, oB0, oB1, 1.0f / lB);
	v_add3_u32 v37, v37, v38, s14
	v_add3_u32 v36, v36, v39, s14
	v_and_b32_e32 v37, 0xffff0000, v37
	v_and_b32_e32 v36, 0xffff0000, v36
	v_or_b32_sdwa v35, v37, v35 dst_sel:DWORD dst_unused:UNUSED_PAD src0_sel:DWORD src1_sel:WORD_1
	v_or_b32_sdwa v34, v36, v34 dst_sel:DWORD dst_unused:UNUSED_PAD src0_sel:DWORD src1_sel:WORD_1
	global_store_dwordx2 v[66:67], v[34:35], off offset:1056
	v_mov_b32_e32 v34, v42
	v_mov_b32_e32 v35, v44
	v_pk_mul_f32 v[34:35], v[34:35], v[68:69] op_sel_hi:[1,0]
	v_mov_b32_e32 v44, v43
	v_pk_mul_f32 v[36:37], v[44:45], v[68:69] op_sel_hi:[1,0]
	v_and_b32_sdwa v38, v35, v243 dst_sel:DWORD dst_unused:UNUSED_PAD src0_sel:WORD_1 src1_sel:DWORD
	v_and_b32_sdwa v39, v34, v243 dst_sel:DWORD dst_unused:UNUSED_PAD src0_sel:WORD_1 src1_sel:DWORD
	v_add3_u32 v34, v34, v39, s14
	v_add3_u32 v35, v35, v38, s14
	v_and_b32_sdwa v38, v37, v243 dst_sel:DWORD dst_unused:UNUSED_PAD src0_sel:WORD_1 src1_sel:DWORD
	v_and_b32_sdwa v39, v36, v243 dst_sel:DWORD dst_unused:UNUSED_PAD src0_sel:WORD_1 src1_sel:DWORD
	v_add3_u32 v37, v37, v38, s14
	v_add3_u32 v36, v36, v39, s14
	v_and_b32_e32 v37, 0xffff0000, v37
	v_and_b32_e32 v36, 0xffff0000, v36
	v_or_b32_sdwa v35, v37, v35 dst_sel:DWORD dst_unused:UNUSED_PAD src0_sel:DWORD src1_sel:WORD_1
	v_or_b32_sdwa v34, v36, v34 dst_sel:DWORD dst_unused:UNUSED_PAD src0_sel:DWORD src1_sel:WORD_1
	global_store_dwordx2 v[66:67], v[34:35], off offset:1120
	v_mov_b32_e32 v34, v62
	v_mov_b32_e32 v35, v64
	v_pk_mul_f32 v[34:35], v[34:35], v[68:69] op_sel_hi:[1,0]
	v_mov_b32_e32 v64, v63
	v_pk_mul_f32 v[36:37], v[64:65], v[68:69] op_sel_hi:[1,0]
	v_and_b32_sdwa v38, v35, v243 dst_sel:DWORD dst_unused:UNUSED_PAD src0_sel:WORD_1 src1_sel:DWORD
	v_and_b32_sdwa v39, v34, v243 dst_sel:DWORD dst_unused:UNUSED_PAD src0_sel:WORD_1 src1_sel:DWORD
	v_add3_u32 v34, v34, v39, s14
	v_add3_u32 v35, v35, v38, s14
	v_and_b32_sdwa v38, v37, v243 dst_sel:DWORD dst_unused:UNUSED_PAD src0_sel:WORD_1 src1_sel:DWORD
	v_and_b32_sdwa v39, v36, v243 dst_sel:DWORD dst_unused:UNUSED_PAD src0_sel:WORD_1 src1_sel:DWORD
	v_add3_u32 v37, v37, v38, s14
	v_add3_u32 v36, v36, v39, s14
	v_and_b32_e32 v37, 0xffff0000, v37
	v_and_b32_e32 v36, 0xffff0000, v36
	v_or_b32_sdwa v35, v37, v35 dst_sel:DWORD dst_unused:UNUSED_PAD src0_sel:DWORD src1_sel:WORD_1
	v_or_b32_sdwa v34, v36, v34 dst_sel:DWORD dst_unused:UNUSED_PAD src0_sel:DWORD src1_sel:WORD_1
	global_store_dwordx2 v[66:67], v[34:35], off offset:1072
	v_mov_b32_e32 v34, v46
	v_mov_b32_e32 v35, v48
	v_pk_mul_f32 v[34:35], v[34:35], v[68:69] op_sel_hi:[1,0]
	v_mov_b32_e32 v48, v47
	v_pk_mul_f32 v[36:37], v[48:49], v[68:69] op_sel_hi:[1,0]
	v_and_b32_sdwa v39, v34, v243 dst_sel:DWORD dst_unused:UNUSED_PAD src0_sel:WORD_1 src1_sel:DWORD
	v_and_b32_sdwa v38, v35, v243 dst_sel:DWORD dst_unused:UNUSED_PAD src0_sel:WORD_1 src1_sel:DWORD
	v_add3_u32 v34, v34, v39, s14
	v_and_b32_sdwa v39, v36, v243 dst_sel:DWORD dst_unused:UNUSED_PAD src0_sel:WORD_1 src1_sel:DWORD
	v_add3_u32 v35, v35, v38, s14
	v_and_b32_sdwa v38, v37, v243 dst_sel:DWORD dst_unused:UNUSED_PAD src0_sel:WORD_1 src1_sel:DWORD
	v_add3_u32 v36, v36, v39, s14
	v_add3_u32 v37, v37, v38, s14
	v_and_b32_e32 v36, 0xffff0000, v36
	v_and_b32_e32 v37, 0xffff0000, v37
	v_or_b32_sdwa v34, v36, v34 dst_sel:DWORD dst_unused:UNUSED_PAD src0_sel:DWORD src1_sel:WORD_1
	v_div_scale_f32 v36, s[44:45], v69, v69, 1.0
	v_or_b32_sdwa v35, v37, v35 dst_sel:DWORD dst_unused:UNUSED_PAD src0_sel:DWORD src1_sel:WORD_1
	v_rcp_f32_e32 v37, v36
	global_store_dwordx2 v[66:67], v[34:35], off offset:1136
	v_lshl_add_u64 v[34:35], v[66:67], 0, s[36:37]
	s_mov_b64 s[44:45], 0
	v_fma_f32 v38, -v36, v37, 1.0
	v_fmac_f32_e32 v37, v38, v37
	v_div_scale_f32 v38, vcc, 1.0, v69, 1.0
	v_mul_f32_e32 v39, v38, v37
	v_fma_f32 v40, -v36, v39, v38
	v_fmac_f32_e32 v39, v40, v37
	v_fma_f32 v36, -v36, v39, v38
	v_div_fmas_f32 v36, v36, v37, v39
	v_div_fixup_f32 v36, v36, v69, 1.0
	v_mov_b32_e32 v38, v18
	v_mov_b32_e32 v39, v20
	v_pk_mul_f32 v[38:39], v[38:39], v[36:37] op_sel_hi:[1,0]
	v_mov_b32_e32 v20, v19
	v_pk_mul_f32 v[18:19], v[20:21], v[36:37] op_sel_hi:[1,0]
	v_and_b32_sdwa v21, v38, v243 dst_sel:DWORD dst_unused:UNUSED_PAD src0_sel:WORD_1 src1_sel:DWORD
	v_add3_u32 v21, v38, v21, s14
	v_and_b32_sdwa v37, v19, v243 dst_sel:DWORD dst_unused:UNUSED_PAD src0_sel:WORD_1 src1_sel:DWORD
	v_and_b32_sdwa v38, v18, v243 dst_sel:DWORD dst_unused:UNUSED_PAD src0_sel:WORD_1 src1_sel:DWORD
	v_and_b32_sdwa v20, v39, v243 dst_sel:DWORD dst_unused:UNUSED_PAD src0_sel:WORD_1 src1_sel:DWORD
	v_add3_u32 v19, v19, v37, s14
	v_add3_u32 v18, v18, v38, s14
	v_add3_u32 v20, v39, v20, s14
	v_and_b32_e32 v19, 0xffff0000, v19
	v_and_b32_e32 v18, 0xffff0000, v18
	v_or_b32_sdwa v19, v19, v20 dst_sel:DWORD dst_unused:UNUSED_PAD src0_sel:DWORD src1_sel:WORD_1
	v_or_b32_sdwa v18, v18, v21 dst_sel:DWORD dst_unused:UNUSED_PAD src0_sel:DWORD src1_sel:WORD_1
	global_store_dwordx2 v[34:35], v[18:19], off offset:1024
	v_mov_b32_e32 v18, v2
	v_mov_b32_e32 v19, v4
	v_pk_mul_f32 v[18:19], v[18:19], v[36:37] op_sel_hi:[1,0]
	v_mov_b32_e32 v4, v3
	v_pk_mul_f32 v[2:3], v[4:5], v[36:37] op_sel_hi:[1,0]
	v_and_b32_sdwa v4, v19, v243 dst_sel:DWORD dst_unused:UNUSED_PAD src0_sel:WORD_1 src1_sel:DWORD
	v_and_b32_sdwa v5, v18, v243 dst_sel:DWORD dst_unused:UNUSED_PAD src0_sel:WORD_1 src1_sel:DWORD
	v_add3_u32 v5, v18, v5, s14
	v_add3_u32 v4, v19, v4, s14
	v_and_b32_sdwa v18, v3, v243 dst_sel:DWORD dst_unused:UNUSED_PAD src0_sel:WORD_1 src1_sel:DWORD
	v_and_b32_sdwa v19, v2, v243 dst_sel:DWORD dst_unused:UNUSED_PAD src0_sel:WORD_1 src1_sel:DWORD
	v_add3_u32 v3, v3, v18, s14
	v_add3_u32 v2, v2, v19, s14
	v_and_b32_e32 v3, 0xffff0000, v3
; __device__ __forceinline__ unsigned pk2(float lo, float hi) { return f2bf(lo) | (f2bf(hi) << 16); }
; __device__ __forceinline__ void attn_store(bf16_t* op  , const f32x16& o0, const f32x16& o1, float inv) {
; #pragma unroll
;     for (int a = 0; a < 4; ++a) {
;         u32x2 w; w.x = pk2(o0[4 * a] * inv, o0[4 * a + 1] * inv); w.y = pk2(o0[4 * a + 2] * inv, o0[4 * a + 3] * inv); *(u32x2*)(op + 8 * a) = w;
;         u32x2 x; x.x = pk2(o1[4 * a] * inv, o1[4 * a + 1] * inv); x.y = pk2(o1[4 * a + 2] * inv, o1[4 * a + 3] * inv); *(u32x2*)(op + 32 + 8 * a) = x;
;     }
; }
	v_and_b32_e32 v2, 0xffff0000, v2
	v_or_b32_sdwa v3, v3, v4 dst_sel:DWORD dst_unused:UNUSED_PAD src0_sel:DWORD src1_sel:WORD_1
	v_or_b32_sdwa v2, v2, v5 dst_sel:DWORD dst_unused:UNUSED_PAD src0_sel:DWORD src1_sel:WORD_1
	global_store_dwordx2 v[34:35], v[2:3], off offset:1088
	v_mov_b32_e32 v2, v22
	v_mov_b32_e32 v3, v24
	v_pk_mul_f32 v[2:3], v[2:3], v[36:37] op_sel_hi:[1,0]
	v_mov_b32_e32 v24, v23
	v_pk_mul_f32 v[4:5], v[24:25], v[36:37] op_sel_hi:[1,0]
	v_and_b32_sdwa v18, v3, v243 dst_sel:DWORD dst_unused:UNUSED_PAD src0_sel:WORD_1 src1_sel:DWORD
	v_and_b32_sdwa v19, v2, v243 dst_sel:DWORD dst_unused:UNUSED_PAD src0_sel:WORD_1 src1_sel:DWORD
	v_add3_u32 v2, v2, v19, s14
	v_add3_u32 v3, v3, v18, s14
	v_and_b32_sdwa v18, v5, v243 dst_sel:DWORD dst_unused:UNUSED_PAD src0_sel:WORD_1 src1_sel:DWORD
	v_and_b32_sdwa v19, v4, v243 dst_sel:DWORD dst_unused:UNUSED_PAD src0_sel:WORD_1 src1_sel:DWORD
	v_add3_u32 v5, v5, v18, s14
	v_add3_u32 v4, v4, v19, s14
	v_and_b32_e32 v5, 0xffff0000, v5
	v_and_b32_e32 v4, 0xffff0000, v4
	v_or_b32_sdwa v3, v5, v3 dst_sel:DWORD dst_unused:UNUSED_PAD src0_sel:DWORD src1_sel:WORD_1
	v_or_b32_sdwa v2, v4, v2 dst_sel:DWORD dst_unused:UNUSED_PAD src0_sel:DWORD src1_sel:WORD_1
	global_store_dwordx2 v[34:35], v[2:3], off offset:1040
	v_mov_b32_e32 v2, v6
	v_mov_b32_e32 v3, v8
	v_pk_mul_f32 v[2:3], v[2:3], v[36:37] op_sel_hi:[1,0]
	v_mov_b32_e32 v8, v7
	v_pk_mul_f32 v[4:5], v[8:9], v[36:37] op_sel_hi:[1,0]
	v_and_b32_sdwa v6, v3, v243 dst_sel:DWORD dst_unused:UNUSED_PAD src0_sel:WORD_1 src1_sel:DWORD
	v_and_b32_sdwa v7, v2, v243 dst_sel:DWORD dst_unused:UNUSED_PAD src0_sel:WORD_1 src1_sel:DWORD
	v_add3_u32 v2, v2, v7, s14
	v_add3_u32 v3, v3, v6, s14
	v_and_b32_sdwa v6, v5, v243 dst_sel:DWORD dst_unused:UNUSED_PAD src0_sel:WORD_1 src1_sel:DWORD
	v_and_b32_sdwa v7, v4, v243 dst_sel:DWORD dst_unused:UNUSED_PAD src0_sel:WORD_1 src1_sel:DWORD
	v_add3_u32 v5, v5, v6, s14
	v_add3_u32 v4, v4, v7, s14
	v_and_b32_e32 v5, 0xffff0000, v5
	v_and_b32_e32 v4, 0xffff0000, v4
	v_or_b32_sdwa v3, v5, v3 dst_sel:DWORD dst_unused:UNUSED_PAD src0_sel:DWORD src1_sel:WORD_1
	v_or_b32_sdwa v2, v4, v2 dst_sel:DWORD dst_unused:UNUSED_PAD src0_sel:DWORD src1_sel:WORD_1
	global_store_dwordx2 v[34:35], v[2:3], off offset:1104
	v_mov_b32_e32 v2, v26
	v_mov_b32_e32 v3, v28
	v_pk_mul_f32 v[2:3], v[2:3], v[36:37] op_sel_hi:[1,0]
	v_mov_b32_e32 v28, v27
	v_pk_mul_f32 v[4:5], v[28:29], v[36:37] op_sel_hi:[1,0]
	v_and_b32_sdwa v6, v3, v243 dst_sel:DWORD dst_unused:UNUSED_PAD src0_sel:WORD_1 src1_sel:DWORD
	v_and_b32_sdwa v7, v2, v243 dst_sel:DWORD dst_unused:UNUSED_PAD src0_sel:WORD_1 src1_sel:DWORD
	v_add3_u32 v2, v2, v7, s14
	v_add3_u32 v3, v3, v6, s14
	v_and_b32_sdwa v6, v5, v243 dst_sel:DWORD dst_unused:UNUSED_PAD src0_sel:WORD_1 src1_sel:DWORD
	v_and_b32_sdwa v7, v4, v243 dst_sel:DWORD dst_unused:UNUSED_PAD src0_sel:WORD_1 src1_sel:DWORD
	v_add3_u32 v5, v5, v6, s14
	v_add3_u32 v4, v4, v7, s14
	v_and_b32_e32 v5, 0xffff0000, v5
	v_and_b32_e32 v4, 0xffff0000, v4
	v_or_b32_sdwa v3, v5, v3 dst_sel:DWORD dst_unused:UNUSED_PAD src0_sel:DWORD src1_sel:WORD_1
	v_or_b32_sdwa v2, v4, v2 dst_sel:DWORD dst_unused:UNUSED_PAD src0_sel:DWORD src1_sel:WORD_1
	global_store_dwordx2 v[34:35], v[2:3], off offset:1056
	v_mov_b32_e32 v2, v10
	v_mov_b32_e32 v3, v12
	v_pk_mul_f32 v[2:3], v[2:3], v[36:37] op_sel_hi:[1,0]
	v_mov_b32_e32 v12, v11
	v_pk_mul_f32 v[4:5], v[12:13], v[36:37] op_sel_hi:[1,0]
	v_and_b32_sdwa v6, v3, v243 dst_sel:DWORD dst_unused:UNUSED_PAD src0_sel:WORD_1 src1_sel:DWORD
	v_and_b32_sdwa v7, v2, v243 dst_sel:DWORD dst_unused:UNUSED_PAD src0_sel:WORD_1 src1_sel:DWORD
	v_add3_u32 v2, v2, v7, s14
	v_add3_u32 v3, v3, v6, s14
	v_and_b32_sdwa v6, v5, v243 dst_sel:DWORD dst_unused:UNUSED_PAD src0_sel:WORD_1 src1_sel:DWORD
	v_and_b32_sdwa v7, v4, v243 dst_sel:DWORD dst_unused:UNUSED_PAD src0_sel:WORD_1 src1_sel:DWORD
	v_add3_u32 v5, v5, v6, s14
	v_add3_u32 v4, v4, v7, s14
	v_and_b32_e32 v5, 0xffff0000, v5
	v_and_b32_e32 v4, 0xffff0000, v4
	v_or_b32_sdwa v3, v5, v3 dst_sel:DWORD dst_unused:UNUSED_PAD src0_sel:DWORD src1_sel:WORD_1
	v_or_b32_sdwa v2, v4, v2 dst_sel:DWORD dst_unused:UNUSED_PAD src0_sel:DWORD src1_sel:WORD_1
	global_store_dwordx2 v[34:35], v[2:3], off offset:1120
	v_mov_b32_e32 v2, v30
	v_mov_b32_e32 v3, v32
	v_pk_mul_f32 v[2:3], v[2:3], v[36:37] op_sel_hi:[1,0]
	v_mov_b32_e32 v32, v31
	v_pk_mul_f32 v[4:5], v[32:33], v[36:37] op_sel_hi:[1,0]
	v_and_b32_sdwa v6, v3, v243 dst_sel:DWORD dst_unused:UNUSED_PAD src0_sel:WORD_1 src1_sel:DWORD
	v_and_b32_sdwa v7, v2, v243 dst_sel:DWORD dst_unused:UNUSED_PAD src0_sel:WORD_1 src1_sel:DWORD
	v_add3_u32 v2, v2, v7, s14
	v_add3_u32 v3, v3, v6, s14
	v_and_b32_sdwa v6, v5, v243 dst_sel:DWORD dst_unused:UNUSED_PAD src0_sel:WORD_1 src1_sel:DWORD
	v_and_b32_sdwa v7, v4, v243 dst_sel:DWORD dst_unused:UNUSED_PAD src0_sel:WORD_1 src1_sel:DWORD
	v_add3_u32 v5, v5, v6, s14
	v_add3_u32 v4, v4, v7, s14
	v_and_b32_e32 v5, 0xffff0000, v5
	v_and_b32_e32 v4, 0xffff0000, v4
	v_or_b32_sdwa v3, v5, v3 dst_sel:DWORD dst_unused:UNUSED_PAD src0_sel:DWORD src1_sel:WORD_1
	v_or_b32_sdwa v2, v4, v2 dst_sel:DWORD dst_unused:UNUSED_PAD src0_sel:DWORD src1_sel:WORD_1
	global_store_dwordx2 v[34:35], v[2:3], off offset:1072
	v_mov_b32_e32 v2, v14
	v_mov_b32_e32 v3, v16
	v_pk_mul_f32 v[2:3], v[2:3], v[36:37] op_sel_hi:[1,0]
	v_mov_b32_e32 v16, v15
	v_pk_mul_f32 v[4:5], v[16:17], v[36:37] op_sel_hi:[1,0]
	v_and_b32_sdwa v6, v3, v243 dst_sel:DWORD dst_unused:UNUSED_PAD src0_sel:WORD_1 src1_sel:DWORD
	v_and_b32_sdwa v7, v2, v243 dst_sel:DWORD dst_unused:UNUSED_PAD src0_sel:WORD_1 src1_sel:DWORD
	v_add3_u32 v2, v2, v7, s14
	v_add3_u32 v3, v3, v6, s14
	v_and_b32_sdwa v6, v5, v243 dst_sel:DWORD dst_unused:UNUSED_PAD src0_sel:WORD_1 src1_sel:DWORD
	v_and_b32_sdwa v7, v4, v243 dst_sel:DWORD dst_unused:UNUSED_PAD src0_sel:WORD_1 src1_sel:DWORD
	v_add3_u32 v5, v5, v6, s14
	v_add3_u32 v4, v4, v7, s14
	v_and_b32_e32 v5, 0xffff0000, v5
	v_and_b32_e32 v4, 0xffff0000, v4
	v_or_b32_sdwa v3, v5, v3 dst_sel:DWORD dst_unused:UNUSED_PAD src0_sel:DWORD src1_sel:WORD_1
	v_or_b32_sdwa v2, v4, v2 dst_sel:DWORD dst_unused:UNUSED_PAD src0_sel:DWORD src1_sel:WORD_1
	s_and_b64 vcc, exec, s[24:25]
	global_store_dwordx2 v[34:35], v[2:3], off offset:1136
	s_cbranch_vccnz .LBB0_304

; #define LAS __attribute__((address_space(3)))
; #define MFMA32(a, b, c) __builtin_amdgcn_mfma_f32_32x32x16_bf16((a), (b), (c), 0, 0, 0)
; __device__ __forceinline__ void softmax2_pv(f32x16& sc, float& m, float& l, f32x16& o0, f32x16& o1, const bf16x8 (&vf)[2][2]) {
;     float tm = fmaxf(fmaxf(sc[0], sc[1]), fmaxf(sc[2], sc[3]));
; #pragma unroll
;     for (int i = 4; i < 16; i += 4) tm = fmaxf(tm, fmaxf(fmaxf(sc[i], sc[i + 1]), fmaxf(sc[i + 2], sc[i + 3])));
;     tm = fmaxf(tm, __shfl_xor(tm, 32));
;     const float mn = fmaxf(m, tm);
;     if (__builtin_amdgcn_ballot_w64(mn > m)) {
;         const float alpha = __builtin_amdgcn_exp2f(m - mn);
;         l *= alpha;
; #pragma unroll
;         for (int i = 0; i < 16; ++i) { o0[i] *= alpha; o1[i] *= alpha; }
;         m = mn;
;     }
; __device__ __forceinline__ void na_task4(const PP P, int idx, LAS float* tbl, int lane) {
;     ...
;     for (int t = 0; t < nkr; ++t) {
;         bf16x8 nk[4], nv[2][2];
;         const int tn = t + 1 < nkr ? t + 1 : t;
;         NA_LOAD(nk, nv, tn);
;         const int kr = rs0 + t;
;         if (kr < endA) {
;             f32x16 sc = {};
; #pragma unroll
;             for (int ds = 0; ds < 4; ++ds) sc = MFMA32(kf[ds], qrA[ds], sc);
;             const int trow = (kr >= rsqA && kr < rsqA + 8) ? kr - qrowA + 7 : 15;
;             const LAS float* tp = tbl + trow * NAT_COLS + colix;
; #pragma unroll
;             for (int i = 0; i < 16; ++i) sc[i] = (sc[i] * (0.125f * LOG2E) + tp[(i & 7) + 16 * (i >> 3)]) + cm[i];
;             softmax2_pv(sc, mA, lA, oA0, oA1, v);
;         }
.LBB0_342:
	s_add_i32 s50, s24, 1
	s_cmp_lt_i32 s24, s49
	s_cselect_b32 s20, s50, s24
	v_mov_b32_e32 v68, 0x30000
	v_mad_u64_u32 v[68:69], s[40:41], s20, v68, v[184:185]
	s_lshl_b32 s20, s20, 6
	global_load_dwordx4 v[132:135], v[68:69], off offset:2048
	global_load_dwordx4 v[136:139], v[68:69], off offset:2080
	global_load_dwordx4 v[140:143], v[68:69], off offset:2112
	global_load_dwordx4 v[144:147], v[68:69], off offset:2144
	v_lshl_add_u64 v[68:69], s[20:21], 1, v[186:187]
	global_load_dwordx4 v[148:151], v[68:69], off
	global_load_dwordx4 v[152:155], v[68:69], off offset:32
	v_add_co_u32_e32 v68, vcc, 0x600000, v68
	s_add_i32 s20, s47, s24
	s_nop 0
	v_addc_co_u32_e32 v69, vcc, 0, v69, vcc
	global_load_dwordx4 v[160:163], v[68:69], off
	global_load_dwordx4 v[164:167], v[68:69], off offset:32
	s_cmp_ge_i32 s20, s25
	s_cbranch_scc1 .LBB0_345
	s_waitcnt vmcnt(8)
	v_mfma_f32_32x32x16_bf16 v[68:83], v[176:179], v[84:87], 0
	v_cmp_ge_i32_e32 vcc, s20, v67
	v_cmp_lt_i32_e64 s[40:41], s20, v216
	s_and_b64 vcc, vcc, s[40:41]
	v_add_u32_e32 v222, 0x80, v219
	v_cndmask_b32_e32 v222, v251, v222, vcc
	v_lshl_add_u32 v226, v222, 2, v215
	v_add_u32_e32 v222, 0x2460, v226
	v_mfma_f32_32x32x16_bf16 v[68:83], v[172:175], v[92:95], v[68:83]
	ds_read2_b32 v[222:223], v222 offset1:1
	v_mfma_f32_32x32x16_bf16 v[68:83], v[168:171], v[100:103], v[68:83]
	v_mfma_f32_32x32x16_bf16 v[68:83], v[156:159], v[108:111], v[68:83]
	s_waitcnt lgkmcnt(0)
	s_nop 10
	v_fmac_f32_e32 v223, 0x3e38aa3b, v69
	v_add_u32_e32 v69, 0x2468, v226
	ds_read2_b32 v[224:225], v69 offset1:1
	v_fmamk_f32 v68, v68, 0x3e38aa3b, v222
	v_add_f32_e32 v222, v195, v68
	v_add_f32_e32 v68, v196, v223
	s_waitcnt lgkmcnt(0)
	v_fmamk_f32 v69, v70, 0x3e38aa3b, v224
	v_fmac_f32_e32 v225, 0x3e38aa3b, v71
	v_add_u32_e32 v71, 0x2470, v226
	v_add_f32_e32 v70, v197, v69
	v_add_f32_e32 v69, v198, v225
	ds_read2_b32 v[224:225], v71 offset1:1
	v_max_f32_e32 v223, v70, v69
	s_waitcnt lgkmcnt(0)
	v_fmamk_f32 v71, v72, 0x3e38aa3b, v224
	v_fmac_f32_e32 v225, 0x3e38aa3b, v73
	v_add_u32_e32 v73, 0x2478, v226
	v_add_f32_e32 v72, v199, v71
	v_add_f32_e32 v71, v200, v225
	ds_read2_b32 v[224:225], v73 offset1:1
	s_waitcnt lgkmcnt(0)
	v_fmac_f32_e32 v225, 0x3e38aa3b, v75
	v_add_u32_e32 v75, 0x24a0, v226
	v_fmamk_f32 v73, v74, 0x3e38aa3b, v224
	v_add_f32_e32 v74, v205, v225
	ds_read2_b32 v[224:225], v75 offset1:1
	v_add_f32_e32 v73, v201, v73
	s_waitcnt lgkmcnt(0)
	v_fmamk_f32 v75, v76, 0x3e38aa3b, v224
	v_fmac_f32_e32 v225, 0x3e38aa3b, v77
	v_add_u32_e32 v77, 0x24a8, v226
	v_add_f32_e32 v76, v206, v75
	v_add_f32_e32 v75, v207, v225
	ds_read2_b32 v[224:225], v77 offset1:1
	s_waitcnt lgkmcnt(0)
	v_fmamk_f32 v77, v78, 0x3e38aa3b, v224
	v_fmac_f32_e32 v225, 0x3e38aa3b, v79
	v_add_u32_e32 v79, 0x24b0, v226
	v_add_f32_e32 v78, v208, v77
	v_add_f32_e32 v77, v209, v225
	ds_read2_b32 v[224:225], v79 offset1:1
	s_waitcnt lgkmcnt(0)
	v_fmamk_f32 v79, v80, 0x3e38aa3b, v224
	v_fmac_f32_e32 v225, 0x3e38aa3b, v81
	v_add_u32_e32 v81, 0x24b8, v226
	v_add_f32_e32 v80, v210, v79
	v_add_f32_e32 v79, v211, v225
	ds_read2_b32 v[224:225], v81 offset1:1
	s_waitcnt lgkmcnt(0)
	v_fmamk_f32 v81, v82, 0x3e38aa3b, v224
	v_fmac_f32_e32 v225, 0x3e38aa3b, v83
	v_max_f32_e32 v224, v73, v74
	v_add_f32_e32 v81, v212, v81
	v_add_f32_e32 v82, v213, v225
	v_max_f32_e32 v83, v222, v68
	v_max3_f32 v224, v72, v71, v224
	v_max3_f32 v83, v83, v223, v224
	v_max_f32_e32 v223, v78, v77
	v_max_f32_e32 v224, v81, v82
	v_max3_f32 v223, v76, v75, v223
	v_max3_f32 v224, v80, v79, v224
	v_max3_f32 v83, v83, v223, v224
	v_mov_b32_e32 v223, v83
	s_nop 1
	v_permlane32_swap_b32_e32 v223, v83
	s_waitcnt lgkmcnt(0)
	v_max3_f32 v83, v221, v83, v223
	v_cmp_gt_f32_e32 vcc, v83, v221
	s_cbranch_vccz .LBB0_348
	v_sub_f32_e32 v221, v221, v83
	v_exp_f32_e32 v224, v221
	v_mov_b32_e32 v221, v83
	v_mul_f32_e32 v66, v66, v224
	v_pk_mul_f32 v[64:65], v[64:65], v[224:225] op_sel_hi:[1,0]
	v_pk_mul_f32 v[62:63], v[62:63], v[224:225] op_sel_hi:[1,0]
	v_pk_mul_f32 v[60:61], v[60:61], v[224:225] op_sel_hi:[1,0]
	v_pk_mul_f32 v[58:59], v[58:59], v[224:225] op_sel_hi:[1,0]
	v_pk_mul_f32 v[56:57], v[56:57], v[224:225] op_sel_hi:[1,0]
	v_pk_mul_f32 v[54:55], v[54:55], v[224:225] op_sel_hi:[1,0]
	v_pk_mul_f32 v[52:53], v[52:53], v[224:225] op_sel_hi:[1,0]
	v_pk_mul_f32 v[50:51], v[50:51], v[224:225] op_sel_hi:[1,0]
	v_pk_mul_f32 v[48:49], v[48:49], v[224:225] op_sel_hi:[1,0]
	v_pk_mul_f32 v[46:47], v[46:47], v[224:225] op_sel_hi:[1,0]
	v_pk_mul_f32 v[44:45], v[44:45], v[224:225] op_sel_hi:[1,0]
	v_pk_mul_f32 v[42:43], v[42:43], v[224:225] op_sel_hi:[1,0]
	v_pk_mul_f32 v[40:41], v[40:41], v[224:225] op_sel_hi:[1,0]
	v_pk_mul_f32 v[38:39], v[38:39], v[224:225] op_sel_hi:[1,0]
	v_pk_mul_f32 v[36:37], v[36:37], v[224:225] op_sel_hi:[1,0]
	v_pk_mul_f32 v[34:35], v[34:35], v[224:225] op_sel_hi:[1,0]
	s_branch .LBB0_349

; #define LAS __attribute__((address_space(3)))
; #define MFMA32(a, b, c) __builtin_amdgcn_mfma_f32_32x32x16_bf16((a), (b), (c), 0, 0, 0)
; __device__ __forceinline__ void softmax2_pv(f32x16& sc, float& m, float& l, f32x16& o0, f32x16& o1, const bf16x8 (&vf)[2][2]) {
;     float tm = fmaxf(fmaxf(sc[0], sc[1]), fmaxf(sc[2], sc[3]));
; #pragma unroll
;     for (int i = 4; i < 16; i += 4) tm = fmaxf(tm, fmaxf(fmaxf(sc[i], sc[i + 1]), fmaxf(sc[i + 2], sc[i + 3])));
;     tm = fmaxf(tm, __shfl_xor(tm, 32));
;     const float mn = fmaxf(m, tm);
;     if (__builtin_amdgcn_ballot_w64(mn > m)) {
;         const float alpha = __builtin_amdgcn_exp2f(m - mn);
;         l *= alpha;
; #pragma unroll
;         for (int i = 0; i < 16; ++i) { o0[i] *= alpha; o1[i] *= alpha; }
;         m = mn;
;     }
; __device__ __forceinline__ void na_task4(const PP P, int idx, LAS float* tbl, int lane) {
;     ...
;         if (kr >= begB) {
;             f32x16 sc = {};
; #pragma unroll
;             for (int ds = 0; ds < 4; ++ds) sc = MFMA32(kf[ds], qrB[ds], sc);
;             const int trow = (kr >= rsqB && kr < rsqB + 8) ? kr - qrowB + 7 : 15;
;             const LAS float* tp = tbl + trow * NAT_COLS + colix;
; #pragma unroll
;             for (int i = 0; i < 16; ++i) sc[i] = (sc[i] * (0.125f * LOG2E) + tp[(i & 7) + 16 * (i >> 3)]) + cm[i];
;             softmax2_pv(sc, mB, lB, oB0, oB1, v);
;         }
.LBB0_346:
	s_waitcnt vmcnt(8)
	v_mfma_f32_32x32x16_bf16 v[68:83], v[176:179], v[88:91], 0
	v_cmp_ge_i32_e32 vcc, s20, v214
	v_cmp_lt_i32_e64 s[40:41], s20, v217
	s_and_b64 vcc, vcc, s[40:41]
	v_mfma_f32_32x32x16_bf16 v[68:83], v[172:175], v[96:99], v[68:83]
	v_cndmask_b32_e32 v172, v251, v219, vcc
	v_lshl_add_u32 v176, v172, 2, v215
	v_add_u32_e32 v172, 0x2460, v176
	v_add_u32_e32 v173, 0x2468, v176
	v_add_u32_e32 v174, 0x2470, v176
	v_add_u32_e32 v175, 0x2478, v176
	v_add_u32_e32 v177, 0x24a0, v176
	v_mfma_f32_32x32x16_bf16 v[68:83], v[168:171], v[104:107], v[68:83]
	ds_read2_b32 v[168:169], v172 offset1:1
	ds_read2_b32 v[170:171], v173 offset1:1
	ds_read2_b32 v[172:173], v174 offset1:1
	ds_read2_b32 v[174:175], v175 offset1:1
	v_mfma_f32_32x32x16_bf16 v[68:83], v[156:159], v[112:115], v[68:83]
	ds_read2_b32 v[158:159], v177 offset1:1
	s_waitcnt lgkmcnt(4)
	s_nop 9
	v_fmamk_f32 v68, v68, 0x3e38aa3b, v168
	v_fmac_f32_e32 v169, 0x3e38aa3b, v69
	s_waitcnt lgkmcnt(3)
	v_fmamk_f32 v69, v70, 0x3e38aa3b, v170
	v_fmac_f32_e32 v171, 0x3e38aa3b, v71
	s_waitcnt lgkmcnt(2)
	v_fmamk_f32 v70, v72, 0x3e38aa3b, v172
	v_fmac_f32_e32 v173, 0x3e38aa3b, v73
	s_waitcnt lgkmcnt(1)
	v_fmamk_f32 v73, v74, 0x3e38aa3b, v174
	v_fmac_f32_e32 v175, 0x3e38aa3b, v75
	v_add_f32_e32 v157, v195, v68
	v_add_u32_e32 v68, 0x24a8, v176
	v_add_f32_e32 v75, v197, v69
	v_add_f32_e32 v74, v198, v171
	v_add_f32_e32 v72, v199, v70
	v_add_f32_e32 v71, v200, v173
	v_add_f32_e32 v70, v201, v73
	v_add_f32_e32 v69, v205, v175
	v_add_u32_e32 v73, 0x24b0, v176
	v_add_u32_e32 v168, 0x24b8, v176
	ds_read2_b32 v[170:171], v68 offset1:1
	ds_read2_b32 v[172:173], v73 offset1:1
	ds_read2_b32 v[174:175], v168 offset1:1
	s_waitcnt lgkmcnt(3)
	v_fmamk_f32 v68, v76, 0x3e38aa3b, v158
	v_add_f32_e32 v168, v206, v68
	s_waitcnt lgkmcnt(2)
	v_fmamk_f32 v68, v78, 0x3e38aa3b, v170
	v_add_f32_e32 v158, v208, v68
	s_waitcnt lgkmcnt(1)
	v_fmamk_f32 v68, v80, 0x3e38aa3b, v172
	v_add_f32_e32 v156, v196, v169
	v_fmac_f32_e32 v171, 0x3e38aa3b, v79
	v_add_f32_e32 v78, v210, v68
	v_fmac_f32_e32 v173, 0x3e38aa3b, v81
	s_waitcnt lgkmcnt(0)
	v_fmamk_f32 v68, v82, 0x3e38aa3b, v174
	v_fmac_f32_e32 v175, 0x3e38aa3b, v83
	v_max_f32_e32 v81, v70, v69
	v_fmac_f32_e32 v159, 0x3e38aa3b, v77
	v_add_f32_e32 v79, v209, v171
	v_add_f32_e32 v76, v212, v68
	v_add_f32_e32 v68, v213, v175
	v_max_f32_e32 v73, v157, v156
	v_max_f32_e32 v80, v75, v74
	v_max3_f32 v81, v72, v71, v81
	v_add_f32_e32 v159, v207, v159
	v_add_f32_e32 v77, v211, v173
	v_max3_f32 v73, v73, v80, v81
	v_max_f32_e32 v80, v158, v79
	v_max_f32_e32 v81, v76, v68
	v_max3_f32 v80, v168, v159, v80
	v_max3_f32 v81, v78, v77, v81
	v_max3_f32 v73, v73, v80, v81
	v_mov_b32_e32 v80, v73
	s_nop 1
	v_permlane32_swap_b32_e32 v80, v73
	s_waitcnt lgkmcnt(0)
	v_max3_f32 v73, v220, v73, v80
	v_cmp_gt_f32_e32 vcc, v73, v220
	s_cbranch_vccz .LBB0_351
	v_sub_f32_e32 v80, v220, v73
	v_exp_f32_e32 v80, v80
	v_mov_b32_e32 v220, v73
	v_mul_f32_e32 v218, v218, v80
	v_pk_mul_f32 v[32:33], v[32:33], v[80:81] op_sel_hi:[1,0]
	v_pk_mul_f32 v[30:31], v[30:31], v[80:81] op_sel_hi:[1,0]
	v_pk_mul_f32 v[28:29], v[28:29], v[80:81] op_sel_hi:[1,0]
	v_pk_mul_f32 v[26:27], v[26:27], v[80:81] op_sel_hi:[1,0]
	v_pk_mul_f32 v[24:25], v[24:25], v[80:81] op_sel_hi:[1,0]
	v_pk_mul_f32 v[22:23], v[22:23], v[80:81] op_sel_hi:[1,0]
	v_pk_mul_f32 v[20:21], v[20:21], v[80:81] op_sel_hi:[1,0]
	v_pk_mul_f32 v[18:19], v[18:19], v[80:81] op_sel_hi:[1,0]
	v_pk_mul_f32 v[16:17], v[16:17], v[80:81] op_sel_hi:[1,0]
	v_pk_mul_f32 v[14:15], v[14:15], v[80:81] op_sel_hi:[1,0]
	v_pk_mul_f32 v[12:13], v[12:13], v[80:81] op_sel_hi:[1,0]
	v_pk_mul_f32 v[10:11], v[10:11], v[80:81] op_sel_hi:[1,0]
	v_pk_mul_f32 v[8:9], v[8:9], v[80:81] op_sel_hi:[1,0]
	v_pk_mul_f32 v[6:7], v[6:7], v[80:81] op_sel_hi:[1,0]
	v_pk_mul_f32 v[4:5], v[4:5], v[80:81] op_sel_hi:[1,0]
	v_pk_mul_f32 v[2:3], v[2:3], v[80:81] op_sel_hi:[1,0]
	s_branch .LBB0_352
